# NA attention: remaining xor-32 ds_bpermute (per-item softmax denominator) replaced by v_permlane32_swap
# speedup vs baseline: 1.0036x; 1.0036x over previous
; __device__ __forceinline__ unsigned cvt_pk_bf16(float lo, float hi) { unsigned r; asm volatile("v_cvt_pk_bf16_f32 %0, %1, %2" : "=v"(r) : "v"(lo), "v"(hi)); return r; }
; __device__ __forceinline__ void na_attn(const Ctx& c, const bf16_t* qkv, const float* rpb, bf16_t* o) {
;     ...
;         for (int e = 0; e < 2; ++e) { const int hd = hh * 16 + 2 * c.wave + e; const float lt = lrun[e] + __shfl_xor(lrun[e], 32), inv = 1.0f / lt;
;             bf16_t* op = o + (size_t)(row_tok + qc) * D + hd * 32 + 4 * h;
; #pragma unroll
;             for (int g = 0; g < 4; ++g) { u32x2 w; w.x = cvt_pk_bf16(O[e][4 * g] * inv, O[e][4 * g + 1] * inv); w.y = cvt_pk_bf16(O[e][4 * g + 2] * inv, O[e][4 * g + 3] * inv); *(u32x2*)(op + 8 * g) = w; } }
.LBB1_437:
	v_mov_b32_e32 v2, v38
	s_nop 1
	v_permlane32_swap_b32 v2, v38
	v_lshlrev_b64 v[0:1], 11, v[126:127]
	v_lshl_add_u64 v[0:1], v[124:125], 0, v[0:1]
	v_lshl_add_u64 v[0:1], s[82:83], 1, v[0:1]
	s_mov_b32 s6, 0
	s_waitcnt lgkmcnt(0)
	v_add_f32_e32 v2, v38, v2
	v_div_scale_f32 v3, s[0:1], v2, v2, 1.0
	v_rcp_f32_e32 v4, v3
	v_div_scale_f32 v38, vcc, 1.0, v2, 1.0
	v_readlane_b32 s68, v254, 38
	v_fma_f32 v40, -v3, v4, 1.0
	v_fmac_f32_e32 v4, v40, v4
	v_mul_f32_e32 v40, v38, v4
	v_fma_f32 v41, -v3, v40, v38
	v_fmac_f32_e32 v40, v41, v4
	v_fma_f32 v3, -v3, v40, v38
	v_div_fmas_f32 v3, v3, v4, v40
	v_div_fixup_f32 v4, v3, v2, 1.0
	v_mul_f32_e32 v2, v22, v4
	v_mul_f32_e32 v3, v23, v4
	v_cvt_pk_bf16_f32 v2, v2, v3
	v_mul_f32_e32 v3, v24, v4
	v_mul_f32_e32 v22, v25, v4
	v_cvt_pk_bf16_f32 v3, v3, v22
	global_store_dwordx2 v[0:1], v[2:3], off
	v_mul_f32_e32 v2, v26, v4
	v_mul_f32_e32 v3, v27, v4
	v_cvt_pk_bf16_f32 v2, v2, v3
	v_mul_f32_e32 v3, v28, v4
	v_mul_f32_e32 v22, v29, v4
	v_cvt_pk_bf16_f32 v3, v3, v22
	global_store_dwordx2 v[0:1], v[2:3], off offset:16
	v_mul_f32_e32 v2, v30, v4
	v_mul_f32_e32 v3, v31, v4
	v_cvt_pk_bf16_f32 v2, v2, v3
	v_mul_f32_e32 v3, v32, v4
	v_mul_f32_e32 v22, v33, v4
	v_cvt_pk_bf16_f32 v3, v3, v22
	global_store_dwordx2 v[0:1], v[2:3], off offset:32
	v_mov_b32_e32 v3, v39
	s_nop 1
	v_permlane32_swap_b32 v3, v39
	v_mul_f32_e32 v2, v34, v4
	v_mul_f32_e32 v22, v35, v4
	v_cvt_pk_bf16_f32 v2, v2, v22
	v_mul_f32_e32 v22, v36, v4
	s_waitcnt lgkmcnt(0)
	v_add_f32_e32 v23, v39, v3
	v_div_scale_f32 v24, s[0:1], v23, v23, 1.0
	v_rcp_f32_e32 v25, v24
	v_mul_f32_e32 v3, v37, v4
	v_cvt_pk_bf16_f32 v3, v22, v3
	global_store_dwordx2 v[0:1], v[2:3], off offset:48
	v_fma_f32 v2, -v24, v25, 1.0
	v_fmac_f32_e32 v25, v2, v25
	v_div_scale_f32 v2, vcc, 1.0, v23, 1.0
	v_mul_f32_e32 v3, v2, v25
	v_fma_f32 v4, -v24, v3, v2
	v_fmac_f32_e32 v3, v4, v25
	v_fma_f32 v2, -v24, v3, v2
	v_div_fmas_f32 v2, v2, v25, v3
	v_div_fixup_f32 v4, v2, v23, 1.0
	v_mul_f32_e32 v2, v6, v4
	v_mul_f32_e32 v3, v7, v4
	v_cvt_pk_bf16_f32 v2, v2, v3
	v_mul_f32_e32 v3, v8, v4
	v_mul_f32_e32 v6, v9, v4
	v_cvt_pk_bf16_f32 v3, v3, v6
	global_store_dwordx2 v[0:1], v[2:3], off offset:64
	v_mul_f32_e32 v2, v10, v4
	v_mul_f32_e32 v3, v11, v4
	v_cvt_pk_bf16_f32 v2, v2, v3
	v_mul_f32_e32 v3, v12, v4
	v_mul_f32_e32 v6, v13, v4
	v_cvt_pk_bf16_f32 v3, v3, v6
	global_store_dwordx2 v[0:1], v[2:3], off offset:80
	v_mul_f32_e32 v2, v14, v4
	v_mul_f32_e32 v3, v15, v4
	v_cvt_pk_bf16_f32 v2, v2, v3
	v_mul_f32_e32 v3, v16, v4
	v_mul_f32_e32 v6, v17, v4
	v_cvt_pk_bf16_f32 v3, v3, v6
	global_store_dwordx2 v[0:1], v[2:3], off offset:96
	v_mul_f32_e32 v2, v18, v4
	v_mul_f32_e32 v3, v19, v4
	v_cvt_pk_bf16_f32 v2, v2, v3
	v_mul_f32_e32 v3, v20, v4
	v_readlane_b32 s83, v255, 32
	v_mul_f32_e32 v4, v21, v4
	v_cvt_pk_bf16_f32 v3, v3, v4
	global_store_dwordx2 v[0:1], v[2:3], off offset:112
